# QKV epilogue plain-tile path: 8 row-scale loads hoisted to the top with one wait (epilogue de-serialisation)
# baseline (speedup 1.0000x reference)
; __device__ __forceinline__ u32x4 pack8(f32x4 a, f32x4 b) { u32x4 w; w.x = cvt_pk_bf16(a[0], a[1]); w.y = cvt_pk_bf16(a[2], a[3]); w.z = cvt_pk_bf16(b[0], b[1]); w.w = cvt_pk_bf16(b[2], b[3]); return w; }
; __device__ __forceinline__ float rs_of(const float* ss, int row) { return 1.0f / sqrtf(ss[row] * (1.0f / 2048.0f) + 1e-5f); }
;     __device__ __forceinline__ void operator()(const f32x4 (&acc)[2][2][4][2], const Unit& u, int wr, int wc, int fr, int fq) const {
;     ...
;             for (int ai = 0; ai < 2; ++ai)
; #pragma unroll
;                 for (int m = 0; m < 4; ++m) {
;                     const int r = row0 + ai * HALF + m * 16, b = r >> 13, s = r & 8191;
;                     const float rr = rs_of(ss, r);
;                     bf16_t* p = Va + (size_t)(b * 8320 + 128 + s) * 256 + wc * 64 + 8 * fq;
; #pragma unroll
;                     for (int bj = 0; bj < 2; ++bj) *(u32x4*)(p + bj * 32) = pack8(acc[ai][bj][m][0] * rr, acc[ai][bj][m][1] * rr);
;                 }
.LBB0_136:
	s_lshl_b32 s5, s0, 8
	s_add_i32 s5, s5, s82
	v_or_b32_e32 v160, s5, v188
	s_movk_i32 s29, 0x1fdf
	v_bitop3_b32 v193, v160, s29, 16 bitop3:0xc8
	s_movk_i32 s29, 0x1fef
	v_or_b32_e32 v182, 16, v160
	v_or_b32_e32 v170, 32, v160
	v_or_b32_e32 v168, 48, v160
	v_add_u32_e32 v166, 0x80, v160
	v_add_u32_e32 v164, 0x90, v160
	v_bitop3_b32 v192, v160, s29, 32 bitop3:0xc8
	s_movk_i32 s29, 0x1fff
	s_mov_b64 s[0:1], -1
	s_cmp_lt_i32 s4, 9
	v_and_b32_e32 v194, 0x1fcf, v160
	v_ashrrev_i32_e32 v161, 31, v160
	v_ashrrev_i32_e32 v183, 31, v182
	v_ashrrev_i32_e32 v171, 31, v170
	v_bitop3_b32 v167, v160, s29, 48 bitop3:0xc8
	v_ashrrev_i32_e32 v169, 31, v168
	v_ashrrev_i32_e32 v191, 13, v166
	v_and_b32_e32 v165, 0x1fcf, v166
	v_and_b32_e32 v163, 0x1fdf, v164
	v_add_u32_e32 v162, 0xa0, v160
	s_cbranch_scc1 .LBB0_138
	v_lshl_add_u64 v[128:129], v[160:161], 2, s[20:21]
	global_load_dword v212, v[128:129], off
	v_lshl_add_u64 v[220:221], v[182:183], 2, s[20:21]
	global_load_dword v213, v[220:221], off
	v_lshl_add_u64 v[222:223], v[170:171], 2, s[20:21]
	global_load_dword v214, v[222:223], off
	v_lshl_add_u64 v[224:225], v[168:169], 2, s[20:21]
	global_load_dword v215, v[224:225], off
	global_load_dword v216, v[128:129], off offset:512
	global_load_dword v217, v[128:129], off offset:576
	global_load_dword v218, v[128:129], off offset:640
	global_load_dword v219, v[128:129], off offset:704
	s_ashr_i32 s0, s5, 13
	s_mul_i32 s29, s0, 0x2080
	s_addk_i32 s29, 0x80
	v_lshlrev_b32_e32 v172, 1, v152
	s_waitcnt vmcnt(0)
	v_fmamk_f32 v130, v212, 0x3a000000, v205
	v_cmp_gt_f32_e32 vcc, s83, v130
	v_mul_f32_e32 v131, 0x4f800000, v130
	s_nop 0
	v_cndmask_b32_e32 v130, v130, v131, vcc
	v_sqrt_f32_e32 v131, v130
	s_nop 0
	v_add_u32_e32 v132, -1, v131
	v_fma_f32 v133, -v132, v131, v130
	v_cmp_ge_f32_e64 s[0:1], 0, v133
	v_add_u32_e32 v133, 1, v131
	s_nop 0
	v_cndmask_b32_e64 v132, v131, v132, s[0:1]
	v_fma_f32 v131, -v133, v131, v130
	v_cmp_lt_f32_e64 s[0:1], 0, v131
	s_nop 1
	v_cndmask_b32_e64 v131, v132, v133, s[0:1]
	v_mul_f32_e32 v132, 0x37800000, v131
	v_cndmask_b32_e32 v131, v131, v132, vcc
	v_cmp_class_f32_e32 vcc, v130, v206
	s_nop 1
	v_cndmask_b32_e32 v130, v131, v130, vcc
	v_div_scale_f32 v131, s[0:1], v130, v130, 1.0
	v_rcp_f32_e32 v132, v131
	s_nop 0
	v_fma_f32 v133, -v131, v132, 1.0
	v_fmac_f32_e32 v132, v133, v132
	v_div_scale_f32 v133, vcc, 1.0, v130, 1.0
	v_mul_f32_e32 v134, v133, v132
	v_fma_f32 v135, -v131, v134, v133
	v_fmac_f32_e32 v134, v135, v132
	v_fma_f32 v131, -v131, v134, v133
	v_div_fmas_f32 v131, v131, v132, v134
	v_div_fixup_f32 v134, v131, v130, 1.0
	v_add_u32_e32 v130, s29, v194
	v_ashrrev_i32_e32 v131, 31, v130
	v_lshlrev_b64 v[130:131], 9, v[130:131]
	v_lshl_add_u64 v[136:137], v[154:155], 0, v[130:131]
	v_pk_mul_f32 v[130:131], v[124:125], v[134:135] op_sel_hi:[1,0]
	v_pk_mul_f32 v[132:133], v[126:127], v[134:135] op_sel_hi:[1,0]
	v_cvt_pk_bf16_f32 v130, v130, v131
	v_pk_mul_f32 v[138:139], v[122:123], v[134:135] op_sel_hi:[1,0]
	v_cvt_pk_bf16_f32 v131, v132, v133
	v_pk_mul_f32 v[140:141], v[120:121], v[134:135] op_sel_hi:[1,0]
	s_nop 0
	v_cvt_pk_bf16_f32 v132, v140, v141
	v_cvt_pk_bf16_f32 v133, v138, v139
	global_store_dwordx4 v[136:137], v[130:133], off
	v_pk_mul_f32 v[138:139], v[114:115], v[134:135] op_sel_hi:[1,0]
	s_nop 0
	v_pk_mul_f32 v[130:131], v[116:117], v[134:135] op_sel_hi:[1,0]
	v_pk_mul_f32 v[132:133], v[118:119], v[134:135] op_sel_hi:[1,0]
	v_cvt_pk_bf16_f32 v130, v130, v131
	v_pk_mul_f32 v[134:135], v[112:113], v[134:135] op_sel_hi:[1,0]
	v_cvt_pk_bf16_f32 v131, v132, v133
	s_nop 0
	v_cvt_pk_bf16_f32 v132, v134, v135
	v_cvt_pk_bf16_f32 v133, v138, v139
	global_store_dwordx4 v[136:137], v[130:133], off offset:64
	s_nop 1
	s_nop 0
	v_fmamk_f32 v130, v213, 0x3a000000, v205
	v_cmp_gt_f32_e32 vcc, s83, v130
	v_mul_f32_e32 v131, 0x4f800000, v130
	s_nop 0
	v_cndmask_b32_e32 v130, v130, v131, vcc
	v_sqrt_f32_e32 v131, v130
	s_nop 0
	v_add_u32_e32 v132, -1, v131
	v_fma_f32 v133, -v132, v131, v130
	v_cmp_ge_f32_e64 s[0:1], 0, v133
	v_add_u32_e32 v133, 1, v131
	s_nop 0
	v_cndmask_b32_e64 v132, v131, v132, s[0:1]
	v_fma_f32 v131, -v133, v131, v130
	v_cmp_lt_f32_e64 s[0:1], 0, v131
	s_nop 1
	v_cndmask_b32_e64 v131, v132, v133, s[0:1]
	v_mul_f32_e32 v132, 0x37800000, v131
	v_cndmask_b32_e32 v131, v131, v132, vcc
	v_cmp_class_f32_e32 vcc, v130, v206
	s_nop 1
	v_cndmask_b32_e32 v130, v131, v130, vcc
	v_div_scale_f32 v131, s[0:1], v130, v130, 1.0
	v_rcp_f32_e32 v132, v131
	s_nop 0
	v_fma_f32 v133, -v131, v132, 1.0
	v_fmac_f32_e32 v132, v133, v132
	v_div_scale_f32 v133, vcc, 1.0, v130, 1.0
	v_mul_f32_e32 v134, v133, v132
	v_fma_f32 v135, -v131, v134, v133
	v_fmac_f32_e32 v134, v135, v132
	v_fma_f32 v131, -v131, v134, v133
	v_div_fmas_f32 v131, v131, v132, v134
	v_div_fixup_f32 v134, v131, v130, 1.0
	v_add_u32_e32 v130, s29, v193
	v_ashrrev_i32_e32 v131, 31, v130
	v_lshlrev_b64 v[130:131], 9, v[130:131]
	v_lshl_add_u64 v[136:137], v[154:155], 0, v[130:131]
	v_pk_mul_f32 v[130:131], v[108:109], v[134:135] op_sel_hi:[1,0]
	v_pk_mul_f32 v[132:133], v[110:111], v[134:135] op_sel_hi:[1,0]
	v_cvt_pk_bf16_f32 v130, v130, v131
	v_pk_mul_f32 v[138:139], v[106:107], v[134:135] op_sel_hi:[1,0]
	v_cvt_pk_bf16_f32 v131, v132, v133
	v_pk_mul_f32 v[140:141], v[104:105], v[134:135] op_sel_hi:[1,0]
	s_nop 0
	v_cvt_pk_bf16_f32 v132, v140, v141
	v_cvt_pk_bf16_f32 v133, v138, v139
	global_store_dwordx4 v[136:137], v[130:133], off
	v_pk_mul_f32 v[138:139], v[98:99], v[134:135] op_sel_hi:[1,0]
	s_nop 0
	v_pk_mul_f32 v[130:131], v[100:101], v[134:135] op_sel_hi:[1,0]
	v_pk_mul_f32 v[132:133], v[102:103], v[134:135] op_sel_hi:[1,0]
	v_cvt_pk_bf16_f32 v130, v130, v131
; __device__ __forceinline__ u32x4 pack8(f32x4 a, f32x4 b) { u32x4 w; w.x = cvt_pk_bf16(a[0], a[1]); w.y = cvt_pk_bf16(a[2], a[3]); w.z = cvt_pk_bf16(b[0], b[1]); w.w = cvt_pk_bf16(b[2], b[3]); return w; }
; __device__ __forceinline__ float rs_of(const float* ss, int row) { return 1.0f / sqrtf(ss[row] * (1.0f / 2048.0f) + 1e-5f); }
;     __device__ __forceinline__ void operator()(const f32x4 (&acc)[2][2][4][2], const Unit& u, int wr, int wc, int fr, int fq) const {
;     ...
;                 for (int m = 0; m < 4; ++m) {
;                     const int r = row0 + ai * HALF + m * 16, b = r >> 13, s = r & 8191;
;                     const float rr = rs_of(ss, r);
;                     bf16_t* p = Va + (size_t)(b * 8320 + 128 + s) * 256 + wc * 64 + 8 * fq;
; #pragma unroll
;                     for (int bj = 0; bj < 2; ++bj) *(u32x4*)(p + bj * 32) = pack8(acc[ai][bj][m][0] * rr, acc[ai][bj][m][1] * rr);
	v_pk_mul_f32 v[134:135], v[96:97], v[134:135] op_sel_hi:[1,0]
	v_cvt_pk_bf16_f32 v131, v132, v133
	s_nop 0
	v_cvt_pk_bf16_f32 v132, v134, v135
	v_cvt_pk_bf16_f32 v133, v138, v139
	global_store_dwordx4 v[136:137], v[130:133], off offset:64
	s_nop 1
	s_nop 0
	v_fmamk_f32 v130, v214, 0x3a000000, v205
	v_cmp_gt_f32_e32 vcc, s83, v130
	v_mul_f32_e32 v131, 0x4f800000, v130
	s_nop 0
	v_cndmask_b32_e32 v130, v130, v131, vcc
	v_sqrt_f32_e32 v131, v130
	s_nop 0
	v_add_u32_e32 v132, -1, v131
	v_fma_f32 v133, -v132, v131, v130
	v_cmp_ge_f32_e64 s[0:1], 0, v133
	v_add_u32_e32 v133, 1, v131
	s_nop 0
	v_cndmask_b32_e64 v132, v131, v132, s[0:1]
	v_fma_f32 v131, -v133, v131, v130
	v_cmp_lt_f32_e64 s[0:1], 0, v131
	s_nop 1
	v_cndmask_b32_e64 v131, v132, v133, s[0:1]
	v_mul_f32_e32 v132, 0x37800000, v131
	v_cndmask_b32_e32 v131, v131, v132, vcc
	v_cmp_class_f32_e32 vcc, v130, v206
	s_nop 1
	v_cndmask_b32_e32 v130, v131, v130, vcc
	v_div_scale_f32 v131, s[0:1], v130, v130, 1.0
	v_rcp_f32_e32 v132, v131
	s_nop 0
	v_fma_f32 v133, -v131, v132, 1.0
	v_fmac_f32_e32 v132, v133, v132
	v_div_scale_f32 v133, vcc, 1.0, v130, 1.0
	v_mul_f32_e32 v134, v133, v132
	v_fma_f32 v135, -v131, v134, v133
	v_fmac_f32_e32 v134, v135, v132
	v_fma_f32 v131, -v131, v134, v133
	v_div_fmas_f32 v131, v131, v132, v134
	v_div_fixup_f32 v134, v131, v130, 1.0
	v_add_u32_e32 v130, s29, v192
	v_ashrrev_i32_e32 v131, 31, v130
	v_lshlrev_b64 v[130:131], 9, v[130:131]
	v_lshl_add_u64 v[136:137], v[154:155], 0, v[130:131]
	v_pk_mul_f32 v[130:131], v[92:93], v[134:135] op_sel_hi:[1,0]
	v_pk_mul_f32 v[132:133], v[94:95], v[134:135] op_sel_hi:[1,0]
	v_cvt_pk_bf16_f32 v130, v130, v131
	v_pk_mul_f32 v[138:139], v[90:91], v[134:135] op_sel_hi:[1,0]
	v_cvt_pk_bf16_f32 v131, v132, v133
	v_pk_mul_f32 v[140:141], v[88:89], v[134:135] op_sel_hi:[1,0]
	s_nop 0
	v_cvt_pk_bf16_f32 v132, v140, v141
	v_cvt_pk_bf16_f32 v133, v138, v139
	global_store_dwordx4 v[136:137], v[130:133], off
	v_pk_mul_f32 v[138:139], v[82:83], v[134:135] op_sel_hi:[1,0]
	s_nop 0
	v_pk_mul_f32 v[130:131], v[84:85], v[134:135] op_sel_hi:[1,0]
	v_pk_mul_f32 v[132:133], v[86:87], v[134:135] op_sel_hi:[1,0]
	v_cvt_pk_bf16_f32 v130, v130, v131
	v_pk_mul_f32 v[134:135], v[80:81], v[134:135] op_sel_hi:[1,0]
	v_cvt_pk_bf16_f32 v131, v132, v133
	s_nop 0
	v_cvt_pk_bf16_f32 v132, v134, v135
	v_cvt_pk_bf16_f32 v133, v138, v139
	global_store_dwordx4 v[136:137], v[130:133], off offset:64
	s_nop 1
	s_nop 0
	v_fmamk_f32 v130, v215, 0x3a000000, v205
	v_cmp_gt_f32_e32 vcc, s83, v130
	v_mul_f32_e32 v131, 0x4f800000, v130
	s_nop 0
	v_cndmask_b32_e32 v130, v130, v131, vcc
	v_sqrt_f32_e32 v131, v130
	s_nop 0
	v_add_u32_e32 v132, -1, v131
	v_fma_f32 v133, -v132, v131, v130
	v_cmp_ge_f32_e64 s[0:1], 0, v133
	v_add_u32_e32 v133, 1, v131
	s_nop 0
	v_cndmask_b32_e64 v132, v131, v132, s[0:1]
	v_fma_f32 v131, -v133, v131, v130
	v_cmp_lt_f32_e64 s[0:1], 0, v131
	s_nop 1
	v_cndmask_b32_e64 v131, v132, v133, s[0:1]
	v_mul_f32_e32 v132, 0x37800000, v131
	v_cndmask_b32_e32 v131, v131, v132, vcc
	v_cmp_class_f32_e32 vcc, v130, v206
	s_nop 1
	v_cndmask_b32_e32 v130, v131, v130, vcc
	v_div_scale_f32 v131, s[0:1], v130, v130, 1.0
	v_rcp_f32_e32 v132, v131
	s_nop 0
	v_fma_f32 v133, -v131, v132, 1.0
	v_fmac_f32_e32 v132, v133, v132
	v_div_scale_f32 v133, vcc, 1.0, v130, 1.0
	v_mul_f32_e32 v134, v133, v132
	v_fma_f32 v135, -v131, v134, v133
	v_fmac_f32_e32 v134, v135, v132
	v_fma_f32 v131, -v131, v134, v133
	v_div_fmas_f32 v131, v131, v132, v134
	v_add_u32_e32 v132, s29, v167
	v_ashrrev_i32_e32 v133, 31, v132
	v_div_fixup_f32 v130, v131, v130, 1.0
	v_lshlrev_b64 v[132:133], 9, v[132:133]
	v_lshl_add_u64 v[136:137], v[154:155], 0, v[132:133]
	v_pk_mul_f32 v[132:133], v[76:77], v[130:131] op_sel_hi:[1,0]
	v_pk_mul_f32 v[134:135], v[78:79], v[130:131] op_sel_hi:[1,0]
	v_cvt_pk_bf16_f32 v132, v132, v133
	v_pk_mul_f32 v[138:139], v[74:75], v[130:131] op_sel_hi:[1,0]
	v_cvt_pk_bf16_f32 v133, v134, v135
	v_pk_mul_f32 v[140:141], v[72:73], v[130:131] op_sel_hi:[1,0]
	s_nop 0
	v_cvt_pk_bf16_f32 v134, v140, v141
	v_cvt_pk_bf16_f32 v135, v138, v139
	global_store_dwordx4 v[136:137], v[132:135], off
	v_pk_mul_f32 v[138:139], v[66:67], v[130:131] op_sel_hi:[1,0]
	v_pk_mul_f32 v[140:141], v[64:65], v[130:131] op_sel_hi:[1,0]
	v_pk_mul_f32 v[132:133], v[70:71], v[130:131] op_sel_hi:[1,0]
	v_pk_mul_f32 v[134:135], v[68:69], v[130:131] op_sel_hi:[1,0]
	s_nop 0
	v_cvt_pk_bf16_f32 v130, v134, v135
	v_cvt_pk_bf16_f32 v131, v132, v133
	v_cvt_pk_bf16_f32 v132, v140, v141
	v_cvt_pk_bf16_f32 v133, v138, v139
	global_store_dwordx4 v[136:137], v[130:133], off offset:64
	s_nop 1
	s_nop 0
	v_mad_i32_i24 v131, v191, s85, v208
	s_nop 0
	v_fmamk_f32 v130, v216, 0x3a000000, v205
	v_cmp_gt_f32_e32 vcc, s83, v130
	v_mul_f32_e32 v132, 0x4f800000, v130
	s_nop 0
	v_cndmask_b32_e32 v130, v130, v132, vcc
	v_sqrt_f32_e32 v132, v130
	s_nop 0
	v_add_u32_e32 v133, -1, v132
	v_fma_f32 v134, -v133, v132, v130
	v_cmp_ge_f32_e64 s[0:1], 0, v134
	v_add_u32_e32 v134, 1, v132
	s_nop 0
	v_cndmask_b32_e64 v133, v132, v133, s[0:1]
	v_fma_f32 v132, -v134, v132, v130
	v_cmp_lt_f32_e64 s[0:1], 0, v132
	s_nop 1
	v_cndmask_b32_e64 v132, v133, v134, s[0:1]
	v_mul_f32_e32 v133, 0x37800000, v132
	v_cndmask_b32_e32 v132, v132, v133, vcc
	v_cmp_class_f32_e32 vcc, v130, v206
	s_nop 1
	v_cndmask_b32_e32 v130, v132, v130, vcc
	v_div_scale_f32 v132, s[0:1], v130, v130, 1.0
	v_rcp_f32_e32 v133, v132
	s_nop 0
	v_fma_f32 v134, -v132, v133, 1.0
	v_fmac_f32_e32 v133, v134, v133
	v_div_scale_f32 v134, vcc, 1.0, v130, 1.0
	v_mul_f32_e32 v135, v134, v133
	v_fma_f32 v136, -v132, v135, v134
	v_fmac_f32_e32 v135, v136, v133
	v_fma_f32 v132, -v132, v135, v134
; __device__ __forceinline__ u32x4 pack8(f32x4 a, f32x4 b) { u32x4 w; w.x = cvt_pk_bf16(a[0], a[1]); w.y = cvt_pk_bf16(a[2], a[3]); w.z = cvt_pk_bf16(b[0], b[1]); w.w = cvt_pk_bf16(b[2], b[3]); return w; }
; __device__ __forceinline__ float rs_of(const float* ss, int row) { return 1.0f / sqrtf(ss[row] * (1.0f / 2048.0f) + 1e-5f); }
;     __device__ __forceinline__ void operator()(const f32x4 (&acc)[2][2][4][2], const Unit& u, int wr, int wc, int fr, int fq) const {
;     ...
;                 for (int m = 0; m < 4; ++m) {
;                     const int r = row0 + ai * HALF + m * 16, b = r >> 13, s = r & 8191;
;                     const float rr = rs_of(ss, r);
;                     bf16_t* p = Va + (size_t)(b * 8320 + 128 + s) * 256 + wc * 64 + 8 * fq;
; #pragma unroll
;                     for (int bj = 0; bj < 2; ++bj) *(u32x4*)(p + bj * 32) = pack8(acc[ai][bj][m][0] * rr, acc[ai][bj][m][1] * rr);
	v_div_fmas_f32 v132, v132, v133, v135
	v_div_fixup_f32 v130, v132, v130, 1.0
	v_add_u32_e32 v132, v131, v165
	v_ashrrev_i32_e32 v133, 31, v132
	v_lshlrev_b64 v[132:133], 9, v[132:133]
	v_lshl_add_u64 v[136:137], v[154:155], 0, v[132:133]
	v_pk_mul_f32 v[134:135], v[62:63], v[130:131] op_sel_hi:[1,0]
	v_pk_mul_f32 v[132:133], v[60:61], v[130:131] op_sel_hi:[1,0]
	v_pk_mul_f32 v[138:139], v[58:59], v[130:131] op_sel_hi:[1,0]
	v_pk_mul_f32 v[140:141], v[56:57], v[130:131] op_sel_hi:[1,0]
	v_cvt_pk_bf16_f32 v132, v132, v133
	v_cvt_pk_bf16_f32 v133, v134, v135
	s_nop 0
	v_cvt_pk_bf16_f32 v134, v140, v141
	v_cvt_pk_bf16_f32 v135, v138, v139
	global_store_dwordx4 v[136:137], v[132:135], off
	v_pk_mul_f32 v[138:139], v[50:51], v[130:131] op_sel_hi:[1,0]
	v_pk_mul_f32 v[140:141], v[48:49], v[130:131] op_sel_hi:[1,0]
	v_pk_mul_f32 v[134:135], v[54:55], v[130:131] op_sel_hi:[1,0]
	v_pk_mul_f32 v[132:133], v[52:53], v[130:131] op_sel_hi:[1,0]
	s_nop 0
	v_cvt_pk_bf16_f32 v132, v132, v133
	v_cvt_pk_bf16_f32 v133, v134, v135
	v_cvt_pk_bf16_f32 v134, v140, v141
	v_cvt_pk_bf16_f32 v135, v138, v139
	global_store_dwordx4 v[136:137], v[132:135], off offset:64
	s_nop 1
	s_nop 0
	v_fmamk_f32 v130, v217, 0x3a000000, v205
	v_cmp_gt_f32_e32 vcc, s83, v130
	v_mul_f32_e32 v132, 0x4f800000, v130
	s_nop 0
	v_cndmask_b32_e32 v130, v130, v132, vcc
	v_sqrt_f32_e32 v132, v130
	s_nop 0
	v_add_u32_e32 v133, -1, v132
	v_fma_f32 v134, -v133, v132, v130
	v_cmp_ge_f32_e64 s[0:1], 0, v134
	v_add_u32_e32 v134, 1, v132
	s_nop 0
	v_cndmask_b32_e64 v133, v132, v133, s[0:1]
	v_fma_f32 v132, -v134, v132, v130
	v_cmp_lt_f32_e64 s[0:1], 0, v132
	s_nop 1
	v_cndmask_b32_e64 v132, v133, v134, s[0:1]
	v_mul_f32_e32 v133, 0x37800000, v132
	v_cndmask_b32_e32 v132, v132, v133, vcc
	v_cmp_class_f32_e32 vcc, v130, v206
	s_nop 1
	v_cndmask_b32_e32 v130, v132, v130, vcc
	v_div_scale_f32 v132, s[0:1], v130, v130, 1.0
	v_rcp_f32_e32 v133, v132
	s_nop 0
	v_fma_f32 v134, -v132, v133, 1.0
	v_fmac_f32_e32 v133, v134, v133
	v_div_scale_f32 v134, vcc, 1.0, v130, 1.0
	v_mul_f32_e32 v135, v134, v133
	v_fma_f32 v136, -v132, v135, v134
	v_fmac_f32_e32 v135, v136, v133
	v_fma_f32 v132, -v132, v135, v134
	v_div_fmas_f32 v132, v132, v133, v135
	v_div_fixup_f32 v130, v132, v130, 1.0
	v_add_u32_e32 v132, v131, v163
	v_ashrrev_i32_e32 v133, 31, v132
	v_lshlrev_b64 v[132:133], 9, v[132:133]
	v_lshl_add_u64 v[136:137], v[154:155], 0, v[132:133]
	v_pk_mul_f32 v[134:135], v[46:47], v[130:131] op_sel_hi:[1,0]
	v_pk_mul_f32 v[132:133], v[44:45], v[130:131] op_sel_hi:[1,0]
	v_pk_mul_f32 v[138:139], v[42:43], v[130:131] op_sel_hi:[1,0]
	v_pk_mul_f32 v[140:141], v[40:41], v[130:131] op_sel_hi:[1,0]
	v_cvt_pk_bf16_f32 v132, v132, v133
	v_cvt_pk_bf16_f32 v133, v134, v135
	s_nop 0
	v_cvt_pk_bf16_f32 v134, v140, v141
	v_cvt_pk_bf16_f32 v135, v138, v139
	global_store_dwordx4 v[136:137], v[132:135], off
	v_pk_mul_f32 v[138:139], v[34:35], v[130:131] op_sel_hi:[1,0]
	v_pk_mul_f32 v[140:141], v[32:33], v[130:131] op_sel_hi:[1,0]
	v_pk_mul_f32 v[134:135], v[38:39], v[130:131] op_sel_hi:[1,0]
	v_pk_mul_f32 v[132:133], v[36:37], v[130:131] op_sel_hi:[1,0]
	s_nop 0
	v_cvt_pk_bf16_f32 v132, v132, v133
	v_cvt_pk_bf16_f32 v133, v134, v135
	v_cvt_pk_bf16_f32 v134, v140, v141
	v_cvt_pk_bf16_f32 v135, v138, v139
	global_store_dwordx4 v[136:137], v[132:135], off offset:64
	s_nop 1
	s_nop 0
	v_fmamk_f32 v130, v218, 0x3a000000, v205
	v_cmp_gt_f32_e32 vcc, s83, v130
	v_mul_f32_e32 v133, 0x4f800000, v130
	v_and_b32_e32 v132, 0x1fef, v162
	v_cndmask_b32_e32 v130, v130, v133, vcc
	v_sqrt_f32_e32 v133, v130
	v_add_u32_e32 v132, v131, v132
	v_add_u32_e32 v134, -1, v133
	v_fma_f32 v135, -v134, v133, v130
	v_cmp_ge_f32_e64 s[0:1], 0, v135
	v_add_u32_e32 v135, 1, v133
	s_nop 0
	v_cndmask_b32_e64 v134, v133, v134, s[0:1]
	v_fma_f32 v133, -v135, v133, v130
	v_cmp_lt_f32_e64 s[0:1], 0, v133
	s_nop 1
; __device__ __forceinline__ u32x4 pack8(f32x4 a, f32x4 b) { u32x4 w; w.x = cvt_pk_bf16(a[0], a[1]); w.y = cvt_pk_bf16(a[2], a[3]); w.z = cvt_pk_bf16(b[0], b[1]); w.w = cvt_pk_bf16(b[2], b[3]); return w; }
; __device__ __forceinline__ float rs_of(const float* ss, int row) { return 1.0f / sqrtf(ss[row] * (1.0f / 2048.0f) + 1e-5f); }
;     __device__ __forceinline__ void operator()(const f32x4 (&acc)[2][2][4][2], const Unit& u, int wr, int wc, int fr, int fq) const {
;     ...
;                 for (int m = 0; m < 4; ++m) {
;                     const int r = row0 + ai * HALF + m * 16, b = r >> 13, s = r & 8191;
;                     const float rr = rs_of(ss, r);
;                     bf16_t* p = Va + (size_t)(b * 8320 + 128 + s) * 256 + wc * 64 + 8 * fq;
; #pragma unroll
;                     for (int bj = 0; bj < 2; ++bj) *(u32x4*)(p + bj * 32) = pack8(acc[ai][bj][m][0] * rr, acc[ai][bj][m][1] * rr);
	v_cndmask_b32_e64 v133, v134, v135, s[0:1]
	v_mul_f32_e32 v134, 0x37800000, v133
	v_cndmask_b32_e32 v133, v133, v134, vcc
	v_cmp_class_f32_e32 vcc, v130, v206
	s_nop 1
	v_cndmask_b32_e32 v130, v133, v130, vcc
	v_div_scale_f32 v133, s[0:1], v130, v130, 1.0
	v_rcp_f32_e32 v134, v133
	s_nop 0
	v_fma_f32 v135, -v133, v134, 1.0
	v_fmac_f32_e32 v134, v135, v134
	v_div_scale_f32 v135, vcc, 1.0, v130, 1.0
	v_mul_f32_e32 v136, v135, v134
	v_fma_f32 v137, -v133, v136, v135
	v_fmac_f32_e32 v136, v137, v134
	v_fma_f32 v133, -v133, v136, v135
	v_div_fmas_f32 v133, v133, v134, v136
	v_div_fixup_f32 v130, v133, v130, 1.0
	v_ashrrev_i32_e32 v133, 31, v132
	v_lshlrev_b64 v[132:133], 9, v[132:133]
	v_lshl_add_u64 v[136:137], v[154:155], 0, v[132:133]
	v_pk_mul_f32 v[134:135], v[30:31], v[130:131] op_sel_hi:[1,0]
	v_pk_mul_f32 v[132:133], v[28:29], v[130:131] op_sel_hi:[1,0]
	v_pk_mul_f32 v[138:139], v[26:27], v[130:131] op_sel_hi:[1,0]
	v_pk_mul_f32 v[140:141], v[24:25], v[130:131] op_sel_hi:[1,0]
	v_cvt_pk_bf16_f32 v132, v132, v133
	v_cvt_pk_bf16_f32 v133, v134, v135
	s_nop 0
	v_cvt_pk_bf16_f32 v134, v140, v141
	v_cvt_pk_bf16_f32 v135, v138, v139
	global_store_dwordx4 v[136:137], v[132:135], off
	v_pk_mul_f32 v[138:139], v[18:19], v[130:131] op_sel_hi:[1,0]
	v_pk_mul_f32 v[140:141], v[16:17], v[130:131] op_sel_hi:[1,0]
	v_pk_mul_f32 v[134:135], v[22:23], v[130:131] op_sel_hi:[1,0]
	v_pk_mul_f32 v[132:133], v[20:21], v[130:131] op_sel_hi:[1,0]
	v_add_u32_e32 v130, 0xb0, v160
	v_cvt_pk_bf16_f32 v132, v132, v133
	v_cvt_pk_bf16_f32 v133, v134, v135
	v_cvt_pk_bf16_f32 v134, v140, v141
	v_cvt_pk_bf16_f32 v135, v138, v139
	global_store_dwordx4 v[136:137], v[132:135], off offset:64
	s_nop 1
	v_and_b32_e32 v130, 0x1fff, v130
	v_add_u32_e32 v130, v131, v130
	v_ashrrev_i32_e32 v131, 31, v130
	v_lshlrev_b64 v[130:131], 9, v[130:131]
	s_nop 0
	v_fmamk_f32 v128, v219, 0x3a000000, v205
	v_cmp_gt_f32_e32 vcc, s83, v128
	v_mul_f32_e32 v129, 0x4f800000, v128
	s_nop 0
	v_cndmask_b32_e32 v128, v128, v129, vcc
	v_sqrt_f32_e32 v129, v128
	s_nop 0
	v_add_u32_e32 v132, -1, v129
	v_fma_f32 v133, -v132, v129, v128
	v_cmp_ge_f32_e64 s[0:1], 0, v133
	v_add_u32_e32 v133, 1, v129
	s_nop 0
	v_cndmask_b32_e64 v132, v129, v132, s[0:1]
	v_fma_f32 v129, -v133, v129, v128
	v_cmp_lt_f32_e64 s[0:1], 0, v129
	s_nop 1
	v_cndmask_b32_e64 v129, v132, v133, s[0:1]
	v_mul_f32_e32 v132, 0x37800000, v129
	v_cndmask_b32_e32 v129, v129, v132, vcc
	v_cmp_class_f32_e32 vcc, v128, v206
	s_nop 1
	v_cndmask_b32_e32 v128, v129, v128, vcc
	v_div_scale_f32 v129, s[0:1], v128, v128, 1.0
	v_rcp_f32_e32 v132, v129
	s_mov_b64 s[0:1], 0
	v_fma_f32 v133, -v129, v132, 1.0
	v_fmac_f32_e32 v132, v133, v132
	v_div_scale_f32 v133, vcc, 1.0, v128, 1.0
	v_mul_f32_e32 v134, v133, v132
	v_fma_f32 v135, -v129, v134, v133
	v_fmac_f32_e32 v134, v135, v132
	v_fma_f32 v129, -v129, v134, v133
	v_div_fmas_f32 v129, v129, v132, v134
	v_div_fixup_f32 v128, v129, v128, 1.0
	v_lshl_add_u64 v[132:133], s[24:25], 0, v[130:131]
	v_lshl_add_u64 v[130:131], v[132:133], 0, v[172:173]
	v_pk_mul_f32 v[136:137], v[14:15], v[128:129] op_sel_hi:[1,0]
	v_pk_mul_f32 v[134:135], v[12:13], v[128:129] op_sel_hi:[1,0]
	v_pk_mul_f32 v[138:139], v[10:11], v[128:129] op_sel_hi:[1,0]
	v_pk_mul_f32 v[140:141], v[8:9], v[128:129] op_sel_hi:[1,0]
	v_cvt_pk_bf16_f32 v134, v134, v135
	v_cvt_pk_bf16_f32 v135, v136, v137
	s_nop 0
	v_cvt_pk_bf16_f32 v136, v140, v141
	v_cvt_pk_bf16_f32 v137, v138, v139
	global_store_dwordx4 v[130:131], v[134:137], off
	v_pk_mul_f32 v[130:131], v[6:7], v[128:129] op_sel_hi:[1,0]
	v_pk_mul_f32 v[138:139], v[0:1], v[128:129] op_sel_hi:[1,0]
	v_pk_mul_f32 v[134:135], v[4:5], v[128:129] op_sel_hi:[1,0]
	v_pk_mul_f32 v[136:137], v[2:3], v[128:129] op_sel_hi:[1,0]
	v_cvt_pk_bf16_f32 v128, v134, v135
	v_cvt_pk_bf16_f32 v129, v130, v131
	v_cvt_pk_bf16_f32 v130, v138, v139
	s_nop 0
	v_cvt_pk_bf16_f32 v131, v136, v137
